# E4 plus per-XCD start offset (s_sleep by blockIdx&7) at the SwiGLU GEMM phase entry to de-phase the XCDs store bursts
# speedup vs baseline: 1.0022x; 1.0006x over previous
.LBB0_1028:
	s_and_b32 vcc_lo, s2, 7
	s_cmp_eq_u32 vcc_lo, 0
	s_cbranch_scc1 .Ldp_gu_done
.Ldp_gu_loop:
	s_sleep 23
	s_sub_u32 vcc_lo, vcc_lo, 1
	s_cmp_lg_u32 vcc_lo, 0
	s_cbranch_scc1 .Ldp_gu_loop
